# conformer conv tail: last 27 LDS input reads batched (were serialized through one register)
# speedup vs baseline: 1.0062x; 1.0000x over previous
; __device__ __forceinline__ float bf2f(bf16_t b) { return __uint_as_float((unsigned)b << 16); }
; __device__ __forceinline__ void conf_unit(const Ctx& X, LAS unsigned char* lds, int b, int c, int tid, int wave, int lane, int layer) {
;     ...
;         const int ch = tid & 255, half = tid >> 8;
;         float acc[32];
; #pragma unroll
;         for (int tk = 0; tk < 32; ++tk) acc[tk] = bias;
; #pragma unroll
;         for (int rr = 0; rr < 62; ++rr) { const float g = bf2f(GL[(half * 32 + rr) * 256 + ch]);
; #pragma unroll
;             for (int tk = 0; tk < 32; ++tk) { const int k = rr - tk; if (k >= 0 && k < 31) acc[tk] += w[k] * g; } }
.LpfC_done:
	v_add3_u32 v11, v83, v7, v8
	ds_read_u16 v7, v11
	ds_read_u16 v8, v11 offset:512
	ds_read_u16 v9, v11 offset:1024
	ds_read_u16 v10, v11 offset:1536
	ds_read_u16 v12, v11 offset:2048
	ds_read_u16 v13, v11 offset:2560
	ds_read_u16 v14, v11 offset:3072
	ds_read_u16 v15, v11 offset:3584
	s_waitcnt lgkmcnt(7)
	v_lshlrev_b32_e32 v7, 16, v7
	v_fma_f32 v7, v82, v7, v52
	s_waitcnt lgkmcnt(6)
	v_lshlrev_b32_e32 v8, 16, v8
	v_fmac_f32_e32 v7, v81, v8
	v_fma_f32 v8, v82, v8, v52
	s_waitcnt lgkmcnt(5)
	v_lshlrev_b32_e32 v9, 16, v9
	v_fmac_f32_e32 v7, v80, v9
	v_fmac_f32_e32 v8, v81, v9
	v_fma_f32 v9, v82, v9, v52
	s_waitcnt lgkmcnt(4)
	v_lshlrev_b32_e32 v10, 16, v10
	ds_read_u16 v16, v11 offset:4096
	ds_read_u16 v17, v11 offset:4608
	ds_read_u16 v18, v11 offset:5120
	ds_read_u16 v19, v11 offset:5632
	ds_read_u16 v20, v11 offset:6144
	ds_read_u16 v21, v11 offset:6656
	ds_read_u16 v22, v11 offset:7168
	ds_read_u16 v23, v11 offset:7680
	v_fmac_f32_e32 v7, v79, v10
	v_fmac_f32_e32 v8, v80, v10
	v_fmac_f32_e32 v9, v81, v10
	v_fma_f32 v10, v82, v10, v52
	s_waitcnt lgkmcnt(11)
	v_lshlrev_b32_e32 v12, 16, v12
	v_fmac_f32_e32 v7, v78, v12
	v_fmac_f32_e32 v8, v79, v12
	v_fmac_f32_e32 v9, v80, v12
	v_fmac_f32_e32 v10, v81, v12
	v_fma_f32 v12, v82, v12, v52
	s_waitcnt lgkmcnt(10)
	v_lshlrev_b32_e32 v13, 16, v13
	v_fmac_f32_e32 v7, v77, v13
	v_fmac_f32_e32 v8, v78, v13
	v_fmac_f32_e32 v9, v79, v13
	v_fmac_f32_e32 v10, v80, v13
	v_fmac_f32_e32 v12, v81, v13
	v_fma_f32 v13, v82, v13, v52
	s_waitcnt lgkmcnt(9)
	v_lshlrev_b32_e32 v14, 16, v14
	v_fmac_f32_e32 v7, v76, v14
	v_fmac_f32_e32 v8, v77, v14
	v_fmac_f32_e32 v9, v78, v14
	v_fmac_f32_e32 v10, v79, v14
	v_fmac_f32_e32 v12, v80, v14
	v_fmac_f32_e32 v13, v81, v14
	v_fma_f32 v14, v82, v14, v52
	s_waitcnt lgkmcnt(8)
	v_lshlrev_b32_e32 v15, 16, v15
	v_fmac_f32_e32 v7, v75, v15
	v_fmac_f32_e32 v8, v76, v15
	v_fmac_f32_e32 v9, v77, v15
	v_fmac_f32_e32 v10, v78, v15
	v_fmac_f32_e32 v12, v79, v15
	v_fmac_f32_e32 v13, v80, v15
	v_fmac_f32_e32 v14, v81, v15
	v_fma_f32 v15, v82, v15, v52
	s_waitcnt lgkmcnt(7)
	v_lshlrev_b32_e32 v16, 16, v16
	v_fmac_f32_e32 v7, v74, v16
	v_fmac_f32_e32 v8, v75, v16
	v_fmac_f32_e32 v9, v76, v16
	v_fmac_f32_e32 v10, v77, v16
	v_fmac_f32_e32 v12, v78, v16
	v_fmac_f32_e32 v13, v79, v16
	v_fmac_f32_e32 v14, v80, v16
	v_fmac_f32_e32 v15, v81, v16
	v_fma_f32 v16, v82, v16, v52
	s_waitcnt lgkmcnt(6)
	v_lshlrev_b32_e32 v17, 16, v17
	v_fmac_f32_e32 v7, v73, v17
	v_fmac_f32_e32 v8, v74, v17
	v_fmac_f32_e32 v9, v75, v17
	v_fmac_f32_e32 v10, v76, v17
	v_fmac_f32_e32 v12, v77, v17
	v_fmac_f32_e32 v13, v78, v17
	v_fmac_f32_e32 v14, v79, v17
	v_fmac_f32_e32 v15, v80, v17
	v_fmac_f32_e32 v16, v81, v17
	v_fma_f32 v17, v82, v17, v52
	s_waitcnt lgkmcnt(5)
	v_lshlrev_b32_e32 v18, 16, v18
	v_fmac_f32_e32 v7, v72, v18
	v_fmac_f32_e32 v8, v73, v18
	v_fmac_f32_e32 v9, v74, v18
	v_fmac_f32_e32 v10, v75, v18
	v_fmac_f32_e32 v12, v76, v18
	v_fmac_f32_e32 v13, v77, v18
	v_fmac_f32_e32 v14, v78, v18
	v_fmac_f32_e32 v15, v79, v18
	v_fmac_f32_e32 v16, v80, v18
	v_fmac_f32_e32 v17, v81, v18
	v_fma_f32 v18, v82, v18, v52
	s_waitcnt lgkmcnt(4)
	v_lshlrev_b32_e32 v19, 16, v19
	ds_read_u16 v24, v11 offset:8192
	ds_read_u16 v25, v11 offset:8704
	ds_read_u16 v26, v11 offset:9216
	ds_read_u16 v27, v11 offset:9728
	ds_read_u16 v28, v11 offset:10240
	ds_read_u16 v29, v11 offset:10752
	ds_read_u16 v30, v11 offset:11264
	ds_read_u16 v31, v11 offset:11776
	v_fmac_f32_e32 v7, v71, v19
	v_fmac_f32_e32 v8, v72, v19
	v_fmac_f32_e32 v9, v73, v19
	v_fmac_f32_e32 v10, v74, v19
	v_fmac_f32_e32 v12, v75, v19
	v_fmac_f32_e32 v13, v76, v19
	v_fmac_f32_e32 v14, v77, v19
	v_fmac_f32_e32 v15, v78, v19
	v_fmac_f32_e32 v16, v79, v19
	v_fmac_f32_e32 v17, v80, v19
	v_fmac_f32_e32 v18, v81, v19
	v_fma_f32 v19, v82, v19, v52
	s_waitcnt lgkmcnt(11)
	v_lshlrev_b32_e32 v20, 16, v20
	v_fmac_f32_e32 v7, v70, v20
	v_fmac_f32_e32 v8, v71, v20
	v_fmac_f32_e32 v9, v72, v20
	v_fmac_f32_e32 v10, v73, v20
	v_fmac_f32_e32 v12, v74, v20
	v_fmac_f32_e32 v13, v75, v20
	v_fmac_f32_e32 v14, v76, v20
	v_fmac_f32_e32 v15, v77, v20
	v_fmac_f32_e32 v16, v78, v20
	v_fmac_f32_e32 v17, v79, v20
	v_fmac_f32_e32 v18, v80, v20
	v_fmac_f32_e32 v19, v81, v20
	v_fma_f32 v20, v82, v20, v52
	s_waitcnt lgkmcnt(10)
	v_lshlrev_b32_e32 v21, 16, v21
	v_fmac_f32_e32 v7, v69, v21
	v_fmac_f32_e32 v8, v70, v21
	v_fmac_f32_e32 v9, v71, v21
	v_fmac_f32_e32 v10, v72, v21
	v_fmac_f32_e32 v12, v73, v21
	v_fmac_f32_e32 v13, v74, v21
	v_fmac_f32_e32 v14, v75, v21
	v_fmac_f32_e32 v15, v76, v21
	v_fmac_f32_e32 v16, v77, v21
	v_fmac_f32_e32 v17, v78, v21
	v_fmac_f32_e32 v18, v79, v21
	v_fmac_f32_e32 v19, v80, v21
	v_fmac_f32_e32 v20, v81, v21
	v_fma_f32 v21, v82, v21, v52
	s_waitcnt lgkmcnt(9)
	v_lshlrev_b32_e32 v22, 16, v22
	v_fmac_f32_e32 v7, v68, v22
	v_fmac_f32_e32 v8, v69, v22
	v_fmac_f32_e32 v9, v70, v22
	v_fmac_f32_e32 v10, v71, v22
	v_fmac_f32_e32 v12, v72, v22
	v_fmac_f32_e32 v13, v73, v22
	v_fmac_f32_e32 v14, v74, v22
	v_fmac_f32_e32 v15, v75, v22
	v_fmac_f32_e32 v16, v76, v22
	v_fmac_f32_e32 v17, v77, v22
	v_fmac_f32_e32 v18, v78, v22
	v_fmac_f32_e32 v19, v79, v22
	v_fmac_f32_e32 v20, v80, v22
	v_fmac_f32_e32 v21, v81, v22
	v_fma_f32 v22, v82, v22, v52
	s_waitcnt lgkmcnt(8)
	v_lshlrev_b32_e32 v23, 16, v23
	v_fmac_f32_e32 v7, v67, v23
	v_fmac_f32_e32 v8, v68, v23
	v_fmac_f32_e32 v9, v69, v23
	v_fmac_f32_e32 v10, v70, v23
	v_fmac_f32_e32 v12, v71, v23
	v_fmac_f32_e32 v13, v72, v23
	v_fmac_f32_e32 v14, v73, v23
	v_fmac_f32_e32 v15, v74, v23
	v_fmac_f32_e32 v16, v75, v23
	v_fmac_f32_e32 v17, v76, v23
	v_fmac_f32_e32 v18, v77, v23
	v_fmac_f32_e32 v19, v78, v23
	v_fmac_f32_e32 v20, v79, v23
	v_fmac_f32_e32 v21, v80, v23
	v_fmac_f32_e32 v22, v81, v23
	v_fma_f32 v23, v82, v23, v52
	s_waitcnt lgkmcnt(7)
; __device__ __forceinline__ float bf2f(bf16_t b) { return __uint_as_float((unsigned)b << 16); }
; __device__ __forceinline__ void conf_unit(const Ctx& X, LAS unsigned char* lds, int b, int c, int tid, int wave, int lane, int layer) {
;     ...
; #pragma unroll
;         for (int rr = 0; rr < 62; ++rr) { const float g = bf2f(GL[(half * 32 + rr) * 256 + ch]);
; #pragma unroll
;             for (int tk = 0; tk < 32; ++tk) { const int k = rr - tk; if (k >= 0 && k < 31) acc[tk] += w[k] * g; } }
	v_lshlrev_b32_e32 v24, 16, v24
	v_fmac_f32_e32 v7, v66, v24
	v_fmac_f32_e32 v8, v67, v24
	v_fmac_f32_e32 v9, v68, v24
	v_fmac_f32_e32 v10, v69, v24
	v_fmac_f32_e32 v12, v70, v24
	v_fmac_f32_e32 v13, v71, v24
	v_fmac_f32_e32 v14, v72, v24
	v_fmac_f32_e32 v15, v73, v24
	v_fmac_f32_e32 v16, v74, v24
	v_fmac_f32_e32 v17, v75, v24
	v_fmac_f32_e32 v18, v76, v24
	v_fmac_f32_e32 v19, v77, v24
	v_fmac_f32_e32 v20, v78, v24
	v_fmac_f32_e32 v21, v79, v24
	v_fmac_f32_e32 v22, v80, v24
	v_fmac_f32_e32 v23, v81, v24
	v_fma_f32 v24, v82, v24, v52
	s_waitcnt lgkmcnt(6)
	v_lshlrev_b32_e32 v25, 16, v25
	v_fmac_f32_e32 v7, v65, v25
	v_fmac_f32_e32 v8, v66, v25
	v_fmac_f32_e32 v9, v67, v25
	v_fmac_f32_e32 v10, v68, v25
	v_fmac_f32_e32 v12, v69, v25
	v_fmac_f32_e32 v13, v70, v25
	v_fmac_f32_e32 v14, v71, v25
	v_fmac_f32_e32 v15, v72, v25
	v_fmac_f32_e32 v16, v73, v25
	v_fmac_f32_e32 v17, v74, v25
	v_fmac_f32_e32 v18, v75, v25
	v_fmac_f32_e32 v19, v76, v25
	v_fmac_f32_e32 v20, v77, v25
	v_fmac_f32_e32 v21, v78, v25
	v_fmac_f32_e32 v22, v79, v25
	v_fmac_f32_e32 v23, v80, v25
	v_fmac_f32_e32 v24, v81, v25
	v_fma_f32 v25, v82, v25, v52
	s_waitcnt lgkmcnt(5)
	v_lshlrev_b32_e32 v26, 16, v26
	v_fmac_f32_e32 v7, v64, v26
	v_fmac_f32_e32 v8, v65, v26
	v_fmac_f32_e32 v9, v66, v26
	v_fmac_f32_e32 v10, v67, v26
	v_fmac_f32_e32 v12, v68, v26
	v_fmac_f32_e32 v13, v69, v26
	v_fmac_f32_e32 v14, v70, v26
	v_fmac_f32_e32 v15, v71, v26
	v_fmac_f32_e32 v16, v72, v26
	v_fmac_f32_e32 v17, v73, v26
	v_fmac_f32_e32 v18, v74, v26
	v_fmac_f32_e32 v19, v75, v26
	v_fmac_f32_e32 v20, v76, v26
	v_fmac_f32_e32 v21, v77, v26
	v_fmac_f32_e32 v22, v78, v26
	v_fmac_f32_e32 v23, v79, v26
	v_fmac_f32_e32 v24, v80, v26
	v_fmac_f32_e32 v25, v81, v26
	v_fma_f32 v26, v82, v26, v52
	s_waitcnt lgkmcnt(4)
	v_lshlrev_b32_e32 v27, 16, v27
	ds_read_u16 v32, v11 offset:12288
	ds_read_u16 v33, v11 offset:12800
	ds_read_u16 v34, v11 offset:13312
	ds_read_u16 v35, v11 offset:13824
	ds_read_u16 v36, v11 offset:14336
	ds_read_u16 v37, v11 offset:14848
	ds_read_u16 v38, v11 offset:15360
	ds_read_u16 v39, v11 offset:15872
	v_fmac_f32_e32 v7, v63, v27
	v_fmac_f32_e32 v8, v64, v27
	v_fmac_f32_e32 v9, v65, v27
	v_fmac_f32_e32 v10, v66, v27
	v_fmac_f32_e32 v12, v67, v27
	v_fmac_f32_e32 v13, v68, v27
	v_fmac_f32_e32 v14, v69, v27
	v_fmac_f32_e32 v15, v70, v27
	v_fmac_f32_e32 v16, v71, v27
	v_fmac_f32_e32 v17, v72, v27
	v_fmac_f32_e32 v18, v73, v27
	v_fmac_f32_e32 v19, v74, v27
	v_fmac_f32_e32 v20, v75, v27
	v_fmac_f32_e32 v21, v76, v27
	v_fmac_f32_e32 v22, v77, v27
	v_fmac_f32_e32 v23, v78, v27
	v_fmac_f32_e32 v24, v79, v27
	v_fmac_f32_e32 v25, v80, v27
	v_fmac_f32_e32 v26, v81, v27
	v_fma_f32 v27, v82, v27, v52
	s_waitcnt lgkmcnt(11)
	v_lshlrev_b32_e32 v28, 16, v28
	v_fmac_f32_e32 v7, v62, v28
	v_fmac_f32_e32 v8, v63, v28
	v_fmac_f32_e32 v9, v64, v28
	v_fmac_f32_e32 v10, v65, v28
	v_fmac_f32_e32 v12, v66, v28
	v_fmac_f32_e32 v13, v67, v28
	v_fmac_f32_e32 v14, v68, v28
	v_fmac_f32_e32 v15, v69, v28
	v_fmac_f32_e32 v16, v70, v28
	v_fmac_f32_e32 v17, v71, v28
	v_fmac_f32_e32 v18, v72, v28
	v_fmac_f32_e32 v19, v73, v28
	v_fmac_f32_e32 v20, v74, v28
	v_fmac_f32_e32 v21, v75, v28
	v_fmac_f32_e32 v22, v76, v28
	v_fmac_f32_e32 v23, v77, v28
	v_fmac_f32_e32 v24, v78, v28
	v_fmac_f32_e32 v25, v79, v28
	v_fmac_f32_e32 v26, v80, v28
	v_fmac_f32_e32 v27, v81, v28
	v_fma_f32 v28, v82, v28, v52
	s_waitcnt lgkmcnt(10)
	v_lshlrev_b32_e32 v29, 16, v29
	v_fmac_f32_e32 v7, v61, v29
	v_fmac_f32_e32 v8, v62, v29
	v_fmac_f32_e32 v9, v63, v29
	v_fmac_f32_e32 v10, v64, v29
	v_fmac_f32_e32 v12, v65, v29
	v_fmac_f32_e32 v13, v66, v29
	v_fmac_f32_e32 v14, v67, v29
	v_fmac_f32_e32 v15, v68, v29
	v_fmac_f32_e32 v16, v69, v29
	v_fmac_f32_e32 v17, v70, v29
	v_fmac_f32_e32 v18, v71, v29
	v_fmac_f32_e32 v19, v72, v29
	v_fmac_f32_e32 v20, v73, v29
	v_fmac_f32_e32 v21, v74, v29
	v_fmac_f32_e32 v22, v75, v29
	v_fmac_f32_e32 v23, v76, v29
	v_fmac_f32_e32 v24, v77, v29
	v_fmac_f32_e32 v25, v78, v29
	v_fmac_f32_e32 v26, v79, v29
	v_fmac_f32_e32 v27, v80, v29
	v_fmac_f32_e32 v28, v81, v29
	v_fma_f32 v29, v82, v29, v52
	s_waitcnt lgkmcnt(9)
	v_lshlrev_b32_e32 v30, 16, v30
	v_fmac_f32_e32 v7, v60, v30
	v_fmac_f32_e32 v8, v61, v30
	v_fmac_f32_e32 v9, v62, v30
	v_fmac_f32_e32 v10, v63, v30
	v_fmac_f32_e32 v12, v64, v30
	v_fmac_f32_e32 v13, v65, v30
	v_fmac_f32_e32 v14, v66, v30
	v_fmac_f32_e32 v15, v67, v30
	v_fmac_f32_e32 v16, v68, v30
	v_fmac_f32_e32 v17, v69, v30
	v_fmac_f32_e32 v18, v70, v30
	v_fmac_f32_e32 v19, v71, v30
	v_fmac_f32_e32 v20, v72, v30
	v_fmac_f32_e32 v21, v73, v30
	v_fmac_f32_e32 v22, v74, v30
	v_fmac_f32_e32 v23, v75, v30
	v_fmac_f32_e32 v24, v76, v30
	v_fmac_f32_e32 v25, v77, v30
	v_fmac_f32_e32 v26, v78, v30
	v_fmac_f32_e32 v27, v79, v30
	v_fmac_f32_e32 v28, v80, v30
	v_fmac_f32_e32 v29, v81, v30
	v_fma_f32 v30, v82, v30, v52
	s_waitcnt lgkmcnt(8)
	v_lshlrev_b32_e32 v31, 16, v31
	v_fmac_f32_e32 v7, v59, v31
	v_fmac_f32_e32 v8, v60, v31
	v_fmac_f32_e32 v9, v61, v31
	v_fmac_f32_e32 v10, v62, v31
	v_fmac_f32_e32 v12, v63, v31
	v_fmac_f32_e32 v13, v64, v31
	v_fmac_f32_e32 v14, v65, v31
	v_fmac_f32_e32 v15, v66, v31
	v_fmac_f32_e32 v16, v67, v31
	v_fmac_f32_e32 v17, v68, v31
	v_fmac_f32_e32 v18, v69, v31
	v_fmac_f32_e32 v19, v70, v31
	v_fmac_f32_e32 v20, v71, v31
	v_fmac_f32_e32 v21, v72, v31
	v_fmac_f32_e32 v22, v73, v31
	v_fmac_f32_e32 v23, v74, v31
	v_fmac_f32_e32 v24, v75, v31
	v_fmac_f32_e32 v25, v76, v31
	v_fmac_f32_e32 v26, v77, v31
	v_fmac_f32_e32 v27, v78, v31
	v_fmac_f32_e32 v28, v79, v31
	v_fmac_f32_e32 v29, v80, v31
	v_fmac_f32_e32 v30, v81, v31
	v_fma_f32 v31, v82, v31, v52
	s_waitcnt lgkmcnt(7)
; __device__ __forceinline__ float bf2f(bf16_t b) { return __uint_as_float((unsigned)b << 16); }
; __device__ __forceinline__ void conf_unit(const Ctx& X, LAS unsigned char* lds, int b, int c, int tid, int wave, int lane, int layer) {
;     ...
; #pragma unroll
;         for (int rr = 0; rr < 62; ++rr) { const float g = bf2f(GL[(half * 32 + rr) * 256 + ch]);
; #pragma unroll
;             for (int tk = 0; tk < 32; ++tk) { const int k = rr - tk; if (k >= 0 && k < 31) acc[tk] += w[k] * g; } }
	v_lshlrev_b32_e32 v32, 16, v32
	v_fmac_f32_e32 v7, v58, v32
	v_fmac_f32_e32 v8, v59, v32
	v_fmac_f32_e32 v9, v60, v32
	v_fmac_f32_e32 v10, v61, v32
	v_fmac_f32_e32 v12, v62, v32
	v_fmac_f32_e32 v13, v63, v32
	v_fmac_f32_e32 v14, v64, v32
	v_fmac_f32_e32 v15, v65, v32
	v_fmac_f32_e32 v16, v66, v32
	v_fmac_f32_e32 v17, v67, v32
	v_fmac_f32_e32 v18, v68, v32
	v_fmac_f32_e32 v19, v69, v32
	v_fmac_f32_e32 v20, v70, v32
	v_fmac_f32_e32 v21, v71, v32
	v_fmac_f32_e32 v22, v72, v32
	v_fmac_f32_e32 v23, v73, v32
	v_fmac_f32_e32 v24, v74, v32
	v_fmac_f32_e32 v25, v75, v32
	v_fmac_f32_e32 v26, v76, v32
	v_fmac_f32_e32 v27, v77, v32
	v_fmac_f32_e32 v28, v78, v32
	v_fmac_f32_e32 v29, v79, v32
	v_fmac_f32_e32 v30, v80, v32
	v_fmac_f32_e32 v31, v81, v32
	v_fma_f32 v32, v82, v32, v52
	s_waitcnt lgkmcnt(6)
	v_lshlrev_b32_e32 v33, 16, v33
	v_fmac_f32_e32 v7, v57, v33
	v_fmac_f32_e32 v8, v58, v33
	v_fmac_f32_e32 v9, v59, v33
	v_fmac_f32_e32 v10, v60, v33
	v_fmac_f32_e32 v12, v61, v33
	v_fmac_f32_e32 v13, v62, v33
	v_fmac_f32_e32 v14, v63, v33
	v_fmac_f32_e32 v15, v64, v33
	v_fmac_f32_e32 v16, v65, v33
	v_fmac_f32_e32 v17, v66, v33
	v_fmac_f32_e32 v18, v67, v33
	v_fmac_f32_e32 v19, v68, v33
	v_fmac_f32_e32 v20, v69, v33
	v_fmac_f32_e32 v21, v70, v33
	v_fmac_f32_e32 v22, v71, v33
	v_fmac_f32_e32 v23, v72, v33
	v_fmac_f32_e32 v24, v73, v33
	v_fmac_f32_e32 v25, v74, v33
	v_fmac_f32_e32 v26, v75, v33
	v_fmac_f32_e32 v27, v76, v33
	v_fmac_f32_e32 v28, v77, v33
	v_fmac_f32_e32 v29, v78, v33
	v_fmac_f32_e32 v30, v79, v33
	v_fmac_f32_e32 v31, v80, v33
	v_fmac_f32_e32 v32, v81, v33
	v_fma_f32 v33, v82, v33, v52
	s_waitcnt lgkmcnt(5)
	v_lshlrev_b32_e32 v34, 16, v34
	v_fmac_f32_e32 v7, v56, v34
	v_fmac_f32_e32 v8, v57, v34
	v_fmac_f32_e32 v9, v58, v34
	v_fmac_f32_e32 v10, v59, v34
	v_fmac_f32_e32 v12, v60, v34
	v_fmac_f32_e32 v13, v61, v34
	v_fmac_f32_e32 v14, v62, v34
	v_fmac_f32_e32 v15, v63, v34
	v_fmac_f32_e32 v16, v64, v34
	v_fmac_f32_e32 v17, v65, v34
	v_fmac_f32_e32 v18, v66, v34
	v_fmac_f32_e32 v19, v67, v34
	v_fmac_f32_e32 v20, v68, v34
	v_fmac_f32_e32 v21, v69, v34
	v_fmac_f32_e32 v22, v70, v34
	v_fmac_f32_e32 v23, v71, v34
	v_fmac_f32_e32 v24, v72, v34
	v_fmac_f32_e32 v25, v73, v34
	v_fmac_f32_e32 v26, v74, v34
	v_fmac_f32_e32 v27, v75, v34
	v_fmac_f32_e32 v28, v76, v34
	v_fmac_f32_e32 v29, v77, v34
	v_fmac_f32_e32 v30, v78, v34
	v_fmac_f32_e32 v31, v79, v34
	v_fmac_f32_e32 v32, v80, v34
	v_fmac_f32_e32 v33, v81, v34
	v_fma_f32 v34, v82, v34, v52
	s_waitcnt lgkmcnt(4)
	v_lshlrev_b32_e32 v35, 16, v35
	v_fmac_f32_e32 v7, v55, v35
	v_fmac_f32_e32 v8, v56, v35
	v_fmac_f32_e32 v9, v57, v35
	v_fmac_f32_e32 v10, v58, v35
	v_fmac_f32_e32 v12, v59, v35
	v_fmac_f32_e32 v13, v60, v35
	v_fmac_f32_e32 v14, v61, v35
	v_fmac_f32_e32 v15, v62, v35
	v_fmac_f32_e32 v16, v63, v35
	v_fmac_f32_e32 v17, v64, v35
	v_fmac_f32_e32 v18, v65, v35
	v_fmac_f32_e32 v19, v66, v35
	v_fmac_f32_e32 v20, v67, v35
	v_fmac_f32_e32 v21, v68, v35
	v_fmac_f32_e32 v22, v69, v35
	v_fmac_f32_e32 v23, v70, v35
	v_fmac_f32_e32 v24, v71, v35
	v_fmac_f32_e32 v25, v72, v35
	v_fmac_f32_e32 v26, v73, v35
	v_fmac_f32_e32 v27, v74, v35
	v_fmac_f32_e32 v28, v75, v35
	v_fmac_f32_e32 v29, v76, v35
	v_fmac_f32_e32 v30, v77, v35
	v_fmac_f32_e32 v31, v78, v35
	v_fmac_f32_e32 v32, v79, v35
	v_fmac_f32_e32 v33, v80, v35
	v_fmac_f32_e32 v34, v81, v35
	v_fma_f32 v35, v82, v35, v52
	s_waitcnt lgkmcnt(3)
	v_lshlrev_b32_e32 v36, 16, v36
	v_fmac_f32_e32 v7, v54, v36
	v_fmac_f32_e32 v8, v55, v36
	v_fmac_f32_e32 v9, v56, v36
	v_fmac_f32_e32 v10, v57, v36
	v_fmac_f32_e32 v12, v58, v36
	v_fmac_f32_e32 v13, v59, v36
	v_fmac_f32_e32 v14, v60, v36
	v_fmac_f32_e32 v15, v61, v36
	v_fmac_f32_e32 v16, v62, v36
	v_fmac_f32_e32 v17, v63, v36
	v_fmac_f32_e32 v18, v64, v36
	v_fmac_f32_e32 v19, v65, v36
	v_fmac_f32_e32 v20, v66, v36
	v_fmac_f32_e32 v21, v67, v36
	v_fmac_f32_e32 v22, v68, v36
	v_fmac_f32_e32 v23, v69, v36
	v_fmac_f32_e32 v24, v70, v36
	v_fmac_f32_e32 v25, v71, v36
	v_fmac_f32_e32 v26, v72, v36
	v_fmac_f32_e32 v27, v73, v36
	v_fmac_f32_e32 v28, v74, v36
	v_fmac_f32_e32 v29, v75, v36
	v_fmac_f32_e32 v30, v76, v36
	v_fmac_f32_e32 v31, v77, v36
	v_fmac_f32_e32 v32, v78, v36
	v_fmac_f32_e32 v33, v79, v36
	v_fmac_f32_e32 v34, v80, v36
	v_fmac_f32_e32 v35, v81, v36
	v_fma_f32 v36, v82, v36, v52
	s_waitcnt lgkmcnt(2)
	v_lshlrev_b32_e32 v37, 16, v37
	v_fmac_f32_e32 v7, v53, v37
	v_fmac_f32_e32 v8, v54, v37
	v_fmac_f32_e32 v9, v55, v37
	v_fmac_f32_e32 v10, v56, v37
	v_fmac_f32_e32 v12, v57, v37
	v_fmac_f32_e32 v13, v58, v37
	v_fmac_f32_e32 v14, v59, v37
	v_fmac_f32_e32 v15, v60, v37
	v_fmac_f32_e32 v16, v61, v37
	v_fmac_f32_e32 v17, v62, v37
	v_fmac_f32_e32 v18, v63, v37
	v_fmac_f32_e32 v19, v64, v37
	v_fmac_f32_e32 v20, v65, v37
	v_fmac_f32_e32 v21, v66, v37
	v_fmac_f32_e32 v22, v67, v37
	v_fmac_f32_e32 v23, v68, v37
	v_fmac_f32_e32 v24, v69, v37
	v_fmac_f32_e32 v25, v70, v37
	v_fmac_f32_e32 v26, v71, v37
	v_fmac_f32_e32 v27, v72, v37
	v_fmac_f32_e32 v28, v73, v37
	v_fmac_f32_e32 v29, v74, v37
	v_fmac_f32_e32 v30, v75, v37
	v_fmac_f32_e32 v31, v76, v37
	v_fmac_f32_e32 v32, v77, v37
	v_fmac_f32_e32 v33, v78, v37
	v_fmac_f32_e32 v34, v79, v37
	v_fmac_f32_e32 v35, v80, v37
	v_fmac_f32_e32 v36, v81, v37
	v_fma_f32 v37, v82, v37, v52
	s_waitcnt lgkmcnt(1)
; __device__ __forceinline__ float bf2f(bf16_t b) { return __uint_as_float((unsigned)b << 16); }
; __device__ __forceinline__ void conf_unit(const Ctx& X, LAS unsigned char* lds, int b, int c, int tid, int wave, int lane, int layer) {
;     ...
; #pragma unroll
;         for (int rr = 0; rr < 62; ++rr) { const float g = bf2f(GL[(half * 32 + rr) * 256 + ch]);
; #pragma unroll
;             for (int tk = 0; tk < 32; ++tk) { const int k = rr - tk; if (k >= 0 && k < 31) acc[tk] += w[k] * g; } }
	v_lshlrev_b32_e32 v38, 16, v38
	v_fmac_f32_e32 v7, v51, v38
	v_fmac_f32_e32 v8, v53, v38
	v_fmac_f32_e32 v9, v54, v38
	v_fmac_f32_e32 v10, v55, v38
	v_fmac_f32_e32 v12, v56, v38
	v_fmac_f32_e32 v13, v57, v38
	v_fmac_f32_e32 v14, v58, v38
	v_fmac_f32_e32 v15, v59, v38
	v_fmac_f32_e32 v16, v60, v38
	v_fmac_f32_e32 v17, v61, v38
	v_fmac_f32_e32 v18, v62, v38
	v_fmac_f32_e32 v19, v63, v38
	v_fmac_f32_e32 v20, v64, v38
	v_fmac_f32_e32 v21, v65, v38
	v_fmac_f32_e32 v22, v66, v38
	v_fmac_f32_e32 v23, v67, v38
	v_fmac_f32_e32 v24, v68, v38
	v_fmac_f32_e32 v25, v69, v38
	v_fmac_f32_e32 v26, v70, v38
	v_fmac_f32_e32 v27, v71, v38
	v_fmac_f32_e32 v28, v72, v38
	v_fmac_f32_e32 v29, v73, v38
	v_fmac_f32_e32 v30, v74, v38
	v_fmac_f32_e32 v31, v75, v38
	v_fmac_f32_e32 v32, v76, v38
	v_fmac_f32_e32 v33, v77, v38
	v_fmac_f32_e32 v34, v78, v38
	v_fmac_f32_e32 v35, v79, v38
	v_fmac_f32_e32 v36, v80, v38
	v_fmac_f32_e32 v37, v81, v38
	v_fma_f32 v38, v82, v38, v52
	s_waitcnt lgkmcnt(0)
	v_lshlrev_b32_e32 v39, 16, v39
	v_fmac_f32_e32 v8, v51, v39
	v_fmac_f32_e32 v9, v53, v39
	v_fmac_f32_e32 v10, v54, v39
	v_fmac_f32_e32 v12, v55, v39
	v_fmac_f32_e32 v13, v56, v39
	v_fmac_f32_e32 v14, v57, v39
	v_fmac_f32_e32 v15, v58, v39
	v_fmac_f32_e32 v16, v59, v39
	v_fmac_f32_e32 v17, v60, v39
	v_fmac_f32_e32 v18, v61, v39
	v_fmac_f32_e32 v19, v62, v39
	v_fmac_f32_e32 v20, v63, v39
	v_fmac_f32_e32 v21, v64, v39
	v_fmac_f32_e32 v22, v65, v39
	v_fmac_f32_e32 v23, v66, v39
	v_fmac_f32_e32 v24, v67, v39
	v_fmac_f32_e32 v25, v68, v39
	v_fmac_f32_e32 v26, v69, v39
	v_fmac_f32_e32 v27, v70, v39
	v_fmac_f32_e32 v28, v71, v39
	v_fmac_f32_e32 v29, v72, v39
	v_fmac_f32_e32 v30, v73, v39
	v_fmac_f32_e32 v31, v74, v39
	v_fmac_f32_e32 v32, v75, v39
	v_fmac_f32_e32 v33, v76, v39
	v_fmac_f32_e32 v34, v77, v39
	v_fmac_f32_e32 v35, v78, v39
	v_fmac_f32_e32 v36, v79, v39
	v_fmac_f32_e32 v37, v80, v39
	v_fmac_f32_e32 v38, v81, v39
	v_fmac_f32_e32 v52, v82, v39
	ds_read_u16 v39, v11 offset:16384
	v_lshlrev_b32_e32 v6, 15, v6
	v_add3_u32 v6, v50, v6, v156
	v_ashrrev_i32_e32 v131, 31, v130
	v_readlane_b32 s1, v254, 45
	s_waitcnt lgkmcnt(0)
	v_lshlrev_b32_e32 v39, 16, v39
	v_fmac_f32_e32 v9, v51, v39
	v_fmac_f32_e32 v10, v53, v39
	v_fmac_f32_e32 v12, v54, v39
	v_fmac_f32_e32 v13, v55, v39
	v_fmac_f32_e32 v14, v56, v39
	v_fmac_f32_e32 v15, v57, v39
	v_fmac_f32_e32 v16, v58, v39
	v_fmac_f32_e32 v17, v59, v39
	v_fmac_f32_e32 v18, v60, v39
	v_fmac_f32_e32 v19, v61, v39
	v_fmac_f32_e32 v20, v62, v39
	v_fmac_f32_e32 v21, v63, v39
	v_fmac_f32_e32 v22, v64, v39
	v_fmac_f32_e32 v23, v65, v39
	v_fmac_f32_e32 v24, v66, v39
	v_fmac_f32_e32 v25, v67, v39
	v_fmac_f32_e32 v26, v68, v39
	v_fmac_f32_e32 v27, v69, v39
	v_fmac_f32_e32 v28, v70, v39
	v_fmac_f32_e32 v29, v71, v39
	v_fmac_f32_e32 v30, v72, v39
	v_fmac_f32_e32 v31, v73, v39
	v_fmac_f32_e32 v32, v74, v39
	v_fmac_f32_e32 v33, v75, v39
	v_fmac_f32_e32 v34, v76, v39
	v_fmac_f32_e32 v35, v77, v39
	v_fmac_f32_e32 v36, v78, v39
	v_fmac_f32_e32 v37, v79, v39
	v_fmac_f32_e32 v38, v80, v39
	v_fmac_f32_e32 v52, v81, v39
	ds_read_u16 v39, v11 offset:16896
	s_add_i32 s1, s1, s16
	s_add_i32 s16, s1, s7
	s_lshl_b64 s[4:5], s[16:17], 11
	v_readlane_b32 s1, v254, 43
	s_waitcnt lgkmcnt(0)
	v_lshlrev_b32_e32 v39, 16, v39
	v_fmac_f32_e32 v10, v51, v39
	v_fmac_f32_e32 v12, v53, v39
	v_fmac_f32_e32 v13, v54, v39
	v_fmac_f32_e32 v14, v55, v39
	v_fmac_f32_e32 v15, v56, v39
	v_fmac_f32_e32 v16, v57, v39
	v_fmac_f32_e32 v17, v58, v39
	v_fmac_f32_e32 v18, v59, v39
	v_fmac_f32_e32 v19, v60, v39
	v_fmac_f32_e32 v20, v61, v39
	v_fmac_f32_e32 v21, v62, v39
	v_fmac_f32_e32 v22, v63, v39
	v_fmac_f32_e32 v23, v64, v39
	v_fmac_f32_e32 v24, v65, v39
	v_fmac_f32_e32 v25, v66, v39
	v_fmac_f32_e32 v26, v67, v39
	v_fmac_f32_e32 v27, v68, v39
	v_fmac_f32_e32 v28, v69, v39
	v_fmac_f32_e32 v29, v70, v39
	v_fmac_f32_e32 v30, v71, v39
	v_fmac_f32_e32 v31, v72, v39
	v_fmac_f32_e32 v32, v73, v39
	v_fmac_f32_e32 v33, v74, v39
	v_fmac_f32_e32 v34, v75, v39
	v_fmac_f32_e32 v35, v76, v39
	v_fmac_f32_e32 v36, v77, v39
	v_fmac_f32_e32 v37, v78, v39
	v_fmac_f32_e32 v38, v79, v39
	v_fmac_f32_e32 v52, v80, v39
	ds_read_u16 v134, v11 offset:17408
	ds_read_u16 v135, v11 offset:17920
	ds_read_u16 v136, v11 offset:18432
	ds_read_u16 v137, v11 offset:18944
	ds_read_u16 v138, v11 offset:19456
	ds_read_u16 v139, v11 offset:19968
	ds_read_u16 v140, v11 offset:20480
	ds_read_u16 v141, v11 offset:20992
	ds_read_u16 v142, v11 offset:21504
	ds_read_u16 v143, v11 offset:22016
	ds_read_u16 v144, v11 offset:22528
	ds_read_u16 v145, v11 offset:23040
	ds_read_u16 v146, v11 offset:23552
	ds_read_u16 v147, v11 offset:24064
	ds_read_u16 v148, v11 offset:24576
	ds_read_u16 v149, v11 offset:25088
	ds_read_u16 v150, v11 offset:25600
	ds_read_u16 v151, v11 offset:26112
	ds_read_u16 v152, v11 offset:26624
	ds_read_u16 v153, v11 offset:27136
	ds_read_u16 v171, v11 offset:27648
	ds_read_u16 v172, v11 offset:28160
	ds_read_u16 v173, v11 offset:28672
	ds_read_u16 v174, v11 offset:29184
	ds_read_u16 v175, v11 offset:29696
	ds_read_u16 v176, v11 offset:30208
	ds_read_u16 v177, v11 offset:30720
	v_mov_b32_e32 v39, v134
	s_nop 0
	s_add_u32 s4, s1, s4
	v_readlane_b32 s1, v254, 44
	s_addc_u32 s5, s1, s5
	s_mov_b64 s[22:23], s[64:65]
	s_waitcnt lgkmcnt(0)
; __device__ __forceinline__ float bf2f(bf16_t b) { return __uint_as_float((unsigned)b << 16); }
; __device__ __forceinline__ void conf_unit(const Ctx& X, LAS unsigned char* lds, int b, int c, int tid, int wave, int lane, int layer) {
;     ...
; #pragma unroll
;         for (int rr = 0; rr < 62; ++rr) { const float g = bf2f(GL[(half * 32 + rr) * 256 + ch]);
; #pragma unroll
;             for (int tk = 0; tk < 32; ++tk) { const int k = rr - tk; if (k >= 0 && k < 31) acc[tk] += w[k] * g; } }
	v_lshlrev_b32_e32 v39, 16, v39
	v_fmac_f32_e32 v12, v51, v39
	v_fmac_f32_e32 v13, v53, v39
	v_fmac_f32_e32 v14, v54, v39
	v_fmac_f32_e32 v15, v55, v39
	v_fmac_f32_e32 v16, v56, v39
	v_fmac_f32_e32 v17, v57, v39
	v_fmac_f32_e32 v18, v58, v39
	v_fmac_f32_e32 v19, v59, v39
	v_fmac_f32_e32 v20, v60, v39
	v_fmac_f32_e32 v21, v61, v39
	v_fmac_f32_e32 v22, v62, v39
	v_fmac_f32_e32 v23, v63, v39
	v_fmac_f32_e32 v24, v64, v39
	v_fmac_f32_e32 v25, v65, v39
	v_fmac_f32_e32 v26, v66, v39
	v_fmac_f32_e32 v27, v67, v39
	v_fmac_f32_e32 v28, v68, v39
	v_fmac_f32_e32 v29, v69, v39
	v_fmac_f32_e32 v30, v70, v39
	v_fmac_f32_e32 v31, v71, v39
	v_fmac_f32_e32 v32, v72, v39
	v_fmac_f32_e32 v33, v73, v39
	v_fmac_f32_e32 v34, v74, v39
	v_fmac_f32_e32 v35, v75, v39
	v_fmac_f32_e32 v36, v76, v39
	v_fmac_f32_e32 v37, v77, v39
	v_fmac_f32_e32 v38, v78, v39
	v_fmac_f32_e32 v52, v79, v39
	v_mov_b32_e32 v39, v135
	s_nop 0
	s_mov_b32 s0, 0
	v_readlane_b32 s19, v255, 26
	s_waitcnt lgkmcnt(0)
	v_lshlrev_b32_e32 v39, 16, v39
	v_fmac_f32_e32 v13, v51, v39
	v_fmac_f32_e32 v14, v53, v39
	v_fmac_f32_e32 v15, v54, v39
	v_fmac_f32_e32 v16, v55, v39
	v_fmac_f32_e32 v17, v56, v39
	v_fmac_f32_e32 v18, v57, v39
	v_fmac_f32_e32 v19, v58, v39
	v_fmac_f32_e32 v20, v59, v39
	v_fmac_f32_e32 v21, v60, v39
	v_fmac_f32_e32 v22, v61, v39
	v_fmac_f32_e32 v23, v62, v39
	v_fmac_f32_e32 v24, v63, v39
	v_fmac_f32_e32 v25, v64, v39
	v_fmac_f32_e32 v26, v65, v39
	v_fmac_f32_e32 v27, v66, v39
	v_fmac_f32_e32 v28, v67, v39
	v_fmac_f32_e32 v29, v68, v39
	v_fmac_f32_e32 v30, v69, v39
	v_fmac_f32_e32 v31, v70, v39
	v_fmac_f32_e32 v32, v71, v39
	v_fmac_f32_e32 v33, v72, v39
	v_fmac_f32_e32 v34, v73, v39
	v_fmac_f32_e32 v35, v74, v39
	v_fmac_f32_e32 v36, v75, v39
	v_fmac_f32_e32 v37, v76, v39
	v_fmac_f32_e32 v38, v77, v39
	v_fmac_f32_e32 v52, v78, v39
	v_mov_b32_e32 v39, v136
	s_nop 0
	s_waitcnt lgkmcnt(0)
	v_lshlrev_b32_e32 v39, 16, v39
	v_fmac_f32_e32 v14, v51, v39
	v_fmac_f32_e32 v15, v53, v39
	v_fmac_f32_e32 v16, v54, v39
	v_fmac_f32_e32 v17, v55, v39
	v_fmac_f32_e32 v18, v56, v39
	v_fmac_f32_e32 v19, v57, v39
	v_fmac_f32_e32 v20, v58, v39
	v_fmac_f32_e32 v21, v59, v39
	v_fmac_f32_e32 v22, v60, v39
	v_fmac_f32_e32 v23, v61, v39
	v_fmac_f32_e32 v24, v62, v39
	v_fmac_f32_e32 v25, v63, v39
	v_fmac_f32_e32 v26, v64, v39
	v_fmac_f32_e32 v27, v65, v39
	v_fmac_f32_e32 v28, v66, v39
	v_fmac_f32_e32 v29, v67, v39
	v_fmac_f32_e32 v30, v68, v39
	v_fmac_f32_e32 v31, v69, v39
	v_fmac_f32_e32 v32, v70, v39
	v_fmac_f32_e32 v33, v71, v39
	v_fmac_f32_e32 v34, v72, v39
	v_fmac_f32_e32 v35, v73, v39
	v_fmac_f32_e32 v36, v74, v39
	v_fmac_f32_e32 v37, v75, v39
	v_fmac_f32_e32 v38, v76, v39
	v_fmac_f32_e32 v52, v77, v39
	v_mov_b32_e32 v39, v137
	s_nop 0
	s_waitcnt lgkmcnt(0)
	v_lshlrev_b32_e32 v39, 16, v39
	v_fmac_f32_e32 v15, v51, v39
	v_fmac_f32_e32 v16, v53, v39
	v_fmac_f32_e32 v17, v54, v39
	v_fmac_f32_e32 v18, v55, v39
	v_fmac_f32_e32 v19, v56, v39
	v_fmac_f32_e32 v20, v57, v39
	v_fmac_f32_e32 v21, v58, v39
	v_fmac_f32_e32 v22, v59, v39
	v_fmac_f32_e32 v23, v60, v39
	v_fmac_f32_e32 v24, v61, v39
	v_fmac_f32_e32 v25, v62, v39
	v_fmac_f32_e32 v26, v63, v39
	v_fmac_f32_e32 v27, v64, v39
	v_fmac_f32_e32 v28, v65, v39
	v_fmac_f32_e32 v29, v66, v39
	v_fmac_f32_e32 v30, v67, v39
	v_fmac_f32_e32 v31, v68, v39
	v_fmac_f32_e32 v32, v69, v39
	v_fmac_f32_e32 v33, v70, v39
	v_fmac_f32_e32 v34, v71, v39
	v_fmac_f32_e32 v35, v72, v39
	v_fmac_f32_e32 v36, v73, v39
	v_fmac_f32_e32 v37, v74, v39
	v_fmac_f32_e32 v38, v75, v39
	v_fmac_f32_e32 v52, v76, v39
	v_mov_b32_e32 v39, v138
	s_nop 0
	s_waitcnt lgkmcnt(0)
	v_lshlrev_b32_e32 v39, 16, v39
	v_fmac_f32_e32 v16, v51, v39
	v_fmac_f32_e32 v17, v53, v39
	v_fmac_f32_e32 v18, v54, v39
	v_fmac_f32_e32 v19, v55, v39
	v_fmac_f32_e32 v20, v56, v39
	v_fmac_f32_e32 v21, v57, v39
	v_fmac_f32_e32 v22, v58, v39
	v_fmac_f32_e32 v23, v59, v39
	v_fmac_f32_e32 v24, v60, v39
	v_fmac_f32_e32 v25, v61, v39
	v_fmac_f32_e32 v26, v62, v39
	v_fmac_f32_e32 v27, v63, v39
	v_fmac_f32_e32 v28, v64, v39
	v_fmac_f32_e32 v29, v65, v39
	v_fmac_f32_e32 v30, v66, v39
	v_fmac_f32_e32 v31, v67, v39
	v_fmac_f32_e32 v32, v68, v39
	v_fmac_f32_e32 v33, v69, v39
	v_fmac_f32_e32 v34, v70, v39
	v_fmac_f32_e32 v35, v71, v39
	v_fmac_f32_e32 v36, v72, v39
	v_fmac_f32_e32 v37, v73, v39
	v_fmac_f32_e32 v38, v74, v39
	v_fmac_f32_e32 v52, v75, v39
	v_mov_b32_e32 v39, v139
	s_nop 0
	s_waitcnt lgkmcnt(0)
	v_lshlrev_b32_e32 v39, 16, v39
	v_fmac_f32_e32 v17, v51, v39
	v_fmac_f32_e32 v18, v53, v39
	v_fmac_f32_e32 v19, v54, v39
	v_fmac_f32_e32 v20, v55, v39
	v_fmac_f32_e32 v21, v56, v39
	v_fmac_f32_e32 v22, v57, v39
	v_fmac_f32_e32 v23, v58, v39
	v_fmac_f32_e32 v24, v59, v39
	v_fmac_f32_e32 v25, v60, v39
	v_fmac_f32_e32 v26, v61, v39
	v_fmac_f32_e32 v27, v62, v39
	v_fmac_f32_e32 v28, v63, v39
	v_fmac_f32_e32 v29, v64, v39
	v_fmac_f32_e32 v30, v65, v39
	v_fmac_f32_e32 v31, v66, v39
	v_fmac_f32_e32 v32, v67, v39
	v_fmac_f32_e32 v33, v68, v39
	v_fmac_f32_e32 v34, v69, v39
	v_fmac_f32_e32 v35, v70, v39
	v_fmac_f32_e32 v36, v71, v39
	v_fmac_f32_e32 v37, v72, v39
	v_fmac_f32_e32 v38, v73, v39
	v_fmac_f32_e32 v52, v74, v39
	v_mov_b32_e32 v39, v140
	s_nop 0
	s_waitcnt lgkmcnt(0)
	v_lshlrev_b32_e32 v39, 16, v39
	v_fmac_f32_e32 v18, v51, v39
	v_fmac_f32_e32 v19, v53, v39
	v_fmac_f32_e32 v20, v54, v39
	v_fmac_f32_e32 v21, v55, v39
	v_fmac_f32_e32 v22, v56, v39
	v_fmac_f32_e32 v23, v57, v39
	v_fmac_f32_e32 v24, v58, v39
	v_fmac_f32_e32 v25, v59, v39
	v_fmac_f32_e32 v26, v60, v39
	v_fmac_f32_e32 v27, v61, v39
	v_fmac_f32_e32 v28, v62, v39
	v_fmac_f32_e32 v29, v63, v39
	v_fmac_f32_e32 v30, v64, v39
	v_fmac_f32_e32 v31, v65, v39
	v_fmac_f32_e32 v32, v66, v39
	v_fmac_f32_e32 v33, v67, v39
	v_fmac_f32_e32 v34, v68, v39
	v_fmac_f32_e32 v35, v69, v39
	v_fmac_f32_e32 v36, v70, v39
	v_fmac_f32_e32 v37, v71, v39
	v_fmac_f32_e32 v38, v72, v39
	v_fmac_f32_e32 v52, v73, v39
	v_mov_b32_e32 v39, v141
	s_nop 0
	s_waitcnt lgkmcnt(0)
; __device__ __forceinline__ float bf2f(bf16_t b) { return __uint_as_float((unsigned)b << 16); }
; __device__ __forceinline__ void conf_unit(const Ctx& X, LAS unsigned char* lds, int b, int c, int tid, int wave, int lane, int layer) {
;     ...
; #pragma unroll
;         for (int rr = 0; rr < 62; ++rr) { const float g = bf2f(GL[(half * 32 + rr) * 256 + ch]);
; #pragma unroll
;             for (int tk = 0; tk < 32; ++tk) { const int k = rr - tk; if (k >= 0 && k < 31) acc[tk] += w[k] * g; } }
	v_lshlrev_b32_e32 v39, 16, v39
	v_fmac_f32_e32 v19, v51, v39
	v_fmac_f32_e32 v20, v53, v39
	v_fmac_f32_e32 v21, v54, v39
	v_fmac_f32_e32 v22, v55, v39
	v_fmac_f32_e32 v23, v56, v39
	v_fmac_f32_e32 v24, v57, v39
	v_fmac_f32_e32 v25, v58, v39
	v_fmac_f32_e32 v26, v59, v39
	v_fmac_f32_e32 v27, v60, v39
	v_fmac_f32_e32 v28, v61, v39
	v_fmac_f32_e32 v29, v62, v39
	v_fmac_f32_e32 v30, v63, v39
	v_fmac_f32_e32 v31, v64, v39
	v_fmac_f32_e32 v32, v65, v39
	v_fmac_f32_e32 v33, v66, v39
	v_fmac_f32_e32 v34, v67, v39
	v_fmac_f32_e32 v35, v68, v39
	v_fmac_f32_e32 v36, v69, v39
	v_fmac_f32_e32 v37, v70, v39
	v_fmac_f32_e32 v38, v71, v39
	v_fmac_f32_e32 v52, v72, v39
	v_mov_b32_e32 v39, v142
	s_nop 0
	s_waitcnt lgkmcnt(0)
	v_lshlrev_b32_e32 v39, 16, v39
	v_fmac_f32_e32 v20, v51, v39
	v_fmac_f32_e32 v21, v53, v39
	v_fmac_f32_e32 v22, v54, v39
	v_fmac_f32_e32 v23, v55, v39
	v_fmac_f32_e32 v24, v56, v39
	v_fmac_f32_e32 v25, v57, v39
	v_fmac_f32_e32 v26, v58, v39
	v_fmac_f32_e32 v27, v59, v39
	v_fmac_f32_e32 v28, v60, v39
	v_fmac_f32_e32 v29, v61, v39
	v_fmac_f32_e32 v30, v62, v39
	v_fmac_f32_e32 v31, v63, v39
	v_fmac_f32_e32 v32, v64, v39
	v_fmac_f32_e32 v33, v65, v39
	v_fmac_f32_e32 v34, v66, v39
	v_fmac_f32_e32 v35, v67, v39
	v_fmac_f32_e32 v36, v68, v39
	v_fmac_f32_e32 v37, v69, v39
	v_fmac_f32_e32 v38, v70, v39
	v_fmac_f32_e32 v52, v71, v39
	v_mov_b32_e32 v39, v143
	s_nop 0
	s_waitcnt lgkmcnt(0)
	v_lshlrev_b32_e32 v39, 16, v39
	v_fmac_f32_e32 v21, v51, v39
	v_fmac_f32_e32 v22, v53, v39
	v_fmac_f32_e32 v23, v54, v39
	v_fmac_f32_e32 v24, v55, v39
	v_fmac_f32_e32 v25, v56, v39
	v_fmac_f32_e32 v26, v57, v39
	v_fmac_f32_e32 v27, v58, v39
	v_fmac_f32_e32 v28, v59, v39
	v_fmac_f32_e32 v29, v60, v39
	v_fmac_f32_e32 v30, v61, v39
	v_fmac_f32_e32 v31, v62, v39
	v_fmac_f32_e32 v32, v63, v39
	v_fmac_f32_e32 v33, v64, v39
	v_fmac_f32_e32 v34, v65, v39
	v_fmac_f32_e32 v35, v66, v39
	v_fmac_f32_e32 v36, v67, v39
	v_fmac_f32_e32 v37, v68, v39
	v_fmac_f32_e32 v38, v69, v39
	v_fmac_f32_e32 v52, v70, v39
	v_mov_b32_e32 v39, v144
	s_nop 0
	s_waitcnt lgkmcnt(0)
	v_lshlrev_b32_e32 v39, 16, v39
	v_fmac_f32_e32 v22, v51, v39
	v_fmac_f32_e32 v23, v53, v39
	v_fmac_f32_e32 v24, v54, v39
	v_fmac_f32_e32 v25, v55, v39
	v_fmac_f32_e32 v26, v56, v39
	v_fmac_f32_e32 v27, v57, v39
	v_fmac_f32_e32 v28, v58, v39
	v_fmac_f32_e32 v29, v59, v39
	v_fmac_f32_e32 v30, v60, v39
	v_fmac_f32_e32 v31, v61, v39
	v_fmac_f32_e32 v32, v62, v39
	v_fmac_f32_e32 v33, v63, v39
	v_fmac_f32_e32 v34, v64, v39
	v_fmac_f32_e32 v35, v65, v39
	v_fmac_f32_e32 v36, v66, v39
	v_fmac_f32_e32 v37, v67, v39
	v_fmac_f32_e32 v38, v68, v39
	v_fmac_f32_e32 v52, v69, v39
	v_mov_b32_e32 v39, v145
	s_nop 0
	s_waitcnt lgkmcnt(0)
	v_lshlrev_b32_e32 v39, 16, v39
	v_fmac_f32_e32 v23, v51, v39
	v_fmac_f32_e32 v24, v53, v39
	v_fmac_f32_e32 v25, v54, v39
	v_fmac_f32_e32 v26, v55, v39
	v_fmac_f32_e32 v27, v56, v39
	v_fmac_f32_e32 v28, v57, v39
	v_fmac_f32_e32 v29, v58, v39
	v_fmac_f32_e32 v30, v59, v39
	v_fmac_f32_e32 v31, v60, v39
	v_fmac_f32_e32 v32, v61, v39
	v_fmac_f32_e32 v33, v62, v39
	v_fmac_f32_e32 v34, v63, v39
	v_fmac_f32_e32 v35, v64, v39
	v_fmac_f32_e32 v36, v65, v39
	v_fmac_f32_e32 v37, v66, v39
	v_fmac_f32_e32 v38, v67, v39
	v_fmac_f32_e32 v52, v68, v39
	v_mov_b32_e32 v39, v146
	s_nop 0
	s_waitcnt lgkmcnt(0)
	v_lshlrev_b32_e32 v39, 16, v39
	v_fmac_f32_e32 v24, v51, v39
	v_fmac_f32_e32 v25, v53, v39
	v_fmac_f32_e32 v26, v54, v39
	v_fmac_f32_e32 v27, v55, v39
	v_fmac_f32_e32 v28, v56, v39
	v_fmac_f32_e32 v29, v57, v39
	v_fmac_f32_e32 v30, v58, v39
	v_fmac_f32_e32 v31, v59, v39
	v_fmac_f32_e32 v32, v60, v39
	v_fmac_f32_e32 v33, v61, v39
	v_fmac_f32_e32 v34, v62, v39
	v_fmac_f32_e32 v35, v63, v39
	v_fmac_f32_e32 v36, v64, v39
	v_fmac_f32_e32 v37, v65, v39
	v_fmac_f32_e32 v38, v66, v39
	v_fmac_f32_e32 v52, v67, v39
	v_mov_b32_e32 v39, v147
	s_nop 0
	s_waitcnt lgkmcnt(0)
	v_lshlrev_b32_e32 v39, 16, v39
	v_fmac_f32_e32 v25, v51, v39
	v_fmac_f32_e32 v26, v53, v39
	v_fmac_f32_e32 v27, v54, v39
	v_fmac_f32_e32 v28, v55, v39
	v_fmac_f32_e32 v29, v56, v39
	v_fmac_f32_e32 v30, v57, v39
	v_fmac_f32_e32 v31, v58, v39
	v_fmac_f32_e32 v32, v59, v39
	v_fmac_f32_e32 v33, v60, v39
	v_fmac_f32_e32 v34, v61, v39
	v_fmac_f32_e32 v35, v62, v39
	v_fmac_f32_e32 v36, v63, v39
	v_fmac_f32_e32 v37, v64, v39
	v_fmac_f32_e32 v38, v65, v39
	v_fmac_f32_e32 v52, v66, v39
	v_mov_b32_e32 v39, v148
	s_nop 0
	s_waitcnt lgkmcnt(0)
	v_lshlrev_b32_e32 v39, 16, v39
	v_fmac_f32_e32 v26, v51, v39
	v_fmac_f32_e32 v27, v53, v39
	v_fmac_f32_e32 v28, v54, v39
	v_fmac_f32_e32 v29, v55, v39
	v_fmac_f32_e32 v30, v56, v39
	v_fmac_f32_e32 v31, v57, v39
	v_fmac_f32_e32 v32, v58, v39
	v_fmac_f32_e32 v33, v59, v39
	v_fmac_f32_e32 v34, v60, v39
	v_fmac_f32_e32 v35, v61, v39
	v_fmac_f32_e32 v36, v62, v39
	v_fmac_f32_e32 v37, v63, v39
	v_fmac_f32_e32 v38, v64, v39
	v_fmac_f32_e32 v52, v65, v39
	v_mov_b32_e32 v39, v149
	s_nop 0
	s_waitcnt lgkmcnt(0)
	v_lshlrev_b32_e32 v39, 16, v39
	v_fmac_f32_e32 v27, v51, v39
	v_fmac_f32_e32 v28, v53, v39
	v_fmac_f32_e32 v29, v54, v39
	v_fmac_f32_e32 v30, v55, v39
	v_fmac_f32_e32 v31, v56, v39
	v_fmac_f32_e32 v32, v57, v39
	v_fmac_f32_e32 v33, v58, v39
	v_fmac_f32_e32 v34, v59, v39
	v_fmac_f32_e32 v35, v60, v39
	v_fmac_f32_e32 v36, v61, v39
	v_fmac_f32_e32 v37, v62, v39
	v_fmac_f32_e32 v38, v63, v39
	v_fmac_f32_e32 v52, v64, v39
	v_mov_b32_e32 v39, v150
	s_nop 0
	s_waitcnt lgkmcnt(0)
; #define LAS __attribute__((address_space(3)))
; __device__ __forceinline__ float bf2f(bf16_t b) { return __uint_as_float((unsigned)b << 16); }
; #define LBAR() do { asm volatile("s_waitcnt lgkmcnt(0)" ::: "memory"); __builtin_amdgcn_s_barrier(); asm volatile("" ::: "memory"); } while (0)
; __device__ __forceinline__ void conf_unit(const Ctx& X, LAS unsigned char* lds, int b, int c, int tid, int wave, int lane, int layer) {
;     ...
; #pragma unroll
;         for (int rr = 0; rr < 62; ++rr) { const float g = bf2f(GL[(half * 32 + rr) * 256 + ch]);
; #pragma unroll
;             for (int tk = 0; tk < 32; ++tk) { const int k = rr - tk; if (k >= 0 && k < 31) acc[tk] += w[k] * g; } }
; #pragma unroll
;         for (int tk = 0; tk < 32; ++tk) Y[(half * 32 + tk) * 256 + ch] = acc[tk];
;     }
;     LBAR();
;     {
;         const f32x4 lw = *((const f32x4*)(X.in[6] + layer * 256) + lane), lb = *((const f32x4*)(X.in[7] + layer * 256) + lane);
; #pragma unroll 2
;         for (int tk = wave * 8; tk < wave * 8 + 8; ++tk) {
;             const f32x4 v = *((const LAS f32x4*)(Y + tk * 256) + lane);
;             const float mu = wave_sum((v.x + v.y) + (v.z + v.w)) * (1.f / 256.f);
;             const f32x4 dv = v - mu;
;             const float var = wave_sum((dv.x * dv.x + dv.y * dv.y) + (dv.z * dv.z + dv.w * dv.w)) * (1.f / 256.f);
	v_lshlrev_b32_e32 v39, 16, v39
	v_fmac_f32_e32 v28, v51, v39
	v_fmac_f32_e32 v29, v53, v39
	v_fmac_f32_e32 v30, v54, v39
	v_fmac_f32_e32 v31, v55, v39
	v_fmac_f32_e32 v32, v56, v39
	v_fmac_f32_e32 v33, v57, v39
	v_fmac_f32_e32 v34, v58, v39
	v_fmac_f32_e32 v35, v59, v39
	v_fmac_f32_e32 v36, v60, v39
	v_fmac_f32_e32 v37, v61, v39
	v_fmac_f32_e32 v38, v62, v39
	v_fmac_f32_e32 v52, v63, v39
	v_mov_b32_e32 v39, v151
	s_nop 0
	s_waitcnt lgkmcnt(0)
	v_lshlrev_b32_e32 v39, 16, v39
	v_fmac_f32_e32 v29, v51, v39
	v_fmac_f32_e32 v30, v53, v39
	v_fmac_f32_e32 v31, v54, v39
	v_fmac_f32_e32 v32, v55, v39
	v_fmac_f32_e32 v33, v56, v39
	v_fmac_f32_e32 v34, v57, v39
	v_fmac_f32_e32 v35, v58, v39
	v_fmac_f32_e32 v36, v59, v39
	v_fmac_f32_e32 v37, v60, v39
	v_fmac_f32_e32 v38, v61, v39
	v_fmac_f32_e32 v52, v62, v39
	v_mov_b32_e32 v39, v152
	s_nop 0
	s_waitcnt lgkmcnt(0)
	v_lshlrev_b32_e32 v39, 16, v39
	v_fmac_f32_e32 v30, v51, v39
	v_fmac_f32_e32 v31, v53, v39
	v_fmac_f32_e32 v32, v54, v39
	v_fmac_f32_e32 v33, v55, v39
	v_fmac_f32_e32 v34, v56, v39
	v_fmac_f32_e32 v35, v57, v39
	v_fmac_f32_e32 v36, v58, v39
	v_fmac_f32_e32 v37, v59, v39
	v_fmac_f32_e32 v38, v60, v39
	v_fmac_f32_e32 v52, v61, v39
	v_mov_b32_e32 v39, v153
	s_nop 0
	s_waitcnt lgkmcnt(0)
	v_lshlrev_b32_e32 v39, 16, v39
	v_fmac_f32_e32 v31, v51, v39
	v_fmac_f32_e32 v32, v53, v39
	v_fmac_f32_e32 v33, v54, v39
	v_fmac_f32_e32 v34, v55, v39
	v_fmac_f32_e32 v35, v56, v39
	v_fmac_f32_e32 v36, v57, v39
	v_fmac_f32_e32 v37, v58, v39
	v_fmac_f32_e32 v38, v59, v39
	v_fmac_f32_e32 v52, v60, v39
	v_mov_b32_e32 v39, v171
	s_nop 0
	s_waitcnt lgkmcnt(0)
	v_lshlrev_b32_e32 v39, 16, v39
	v_fmac_f32_e32 v32, v51, v39
	v_fmac_f32_e32 v33, v53, v39
	v_fmac_f32_e32 v34, v54, v39
	v_fmac_f32_e32 v35, v55, v39
	v_fmac_f32_e32 v36, v56, v39
	v_fmac_f32_e32 v37, v57, v39
	v_fmac_f32_e32 v38, v58, v39
	v_fmac_f32_e32 v52, v59, v39
	v_mov_b32_e32 v39, v172
	s_nop 0
	s_waitcnt lgkmcnt(0)
	v_lshlrev_b32_e32 v39, 16, v39
	v_fmac_f32_e32 v33, v51, v39
	v_fmac_f32_e32 v34, v53, v39
	v_fmac_f32_e32 v35, v54, v39
	v_fmac_f32_e32 v36, v55, v39
	v_fmac_f32_e32 v37, v56, v39
	v_fmac_f32_e32 v38, v57, v39
	v_fmac_f32_e32 v52, v58, v39
	v_mov_b32_e32 v39, v173
	s_nop 0
	s_waitcnt lgkmcnt(0)
	v_lshlrev_b32_e32 v39, 16, v39
	v_fmac_f32_e32 v34, v51, v39
	v_fmac_f32_e32 v35, v53, v39
	v_fmac_f32_e32 v36, v54, v39
	v_fmac_f32_e32 v37, v55, v39
	v_fmac_f32_e32 v38, v56, v39
	v_fmac_f32_e32 v52, v57, v39
	v_mov_b32_e32 v39, v174
	s_nop 0
	s_waitcnt lgkmcnt(0)
	v_lshlrev_b32_e32 v39, 16, v39
	v_fmac_f32_e32 v35, v51, v39
	v_fmac_f32_e32 v36, v53, v39
	v_fmac_f32_e32 v37, v54, v39
	v_fmac_f32_e32 v38, v55, v39
	v_fmac_f32_e32 v52, v56, v39
	v_mov_b32_e32 v39, v175
	s_nop 0
	s_waitcnt lgkmcnt(0)
	v_lshlrev_b32_e32 v39, 16, v39
	v_fmac_f32_e32 v36, v51, v39
	v_fmac_f32_e32 v37, v53, v39
	v_fmac_f32_e32 v38, v54, v39
	v_fmac_f32_e32 v52, v55, v39
	v_mov_b32_e32 v39, v176
	s_nop 0
	s_waitcnt lgkmcnt(0)
	v_lshlrev_b32_e32 v39, 16, v39
	v_fmac_f32_e32 v37, v51, v39
	v_fmac_f32_e32 v38, v53, v39
	v_fmac_f32_e32 v52, v54, v39
	v_mov_b32_e32 v39, v177
	s_nop 0
	ds_read_u16 v11, v11 offset:31232
	s_waitcnt lgkmcnt(1)
	v_lshlrev_b32_e32 v39, 16, v39
	v_fmac_f32_e32 v52, v53, v39
	s_waitcnt lgkmcnt(0)
	v_lshlrev_b32_e32 v11, 16, v11
	v_fmac_f32_e32 v38, v51, v39
	v_fmac_f32_e32 v52, v51, v11
	ds_write2st64_b32 v6, v7, v8 offset1:4
	ds_write2st64_b32 v6, v9, v10 offset0:8 offset1:12
	ds_write2st64_b32 v6, v12, v13 offset0:16 offset1:20
	ds_write2st64_b32 v6, v14, v15 offset0:24 offset1:28
	ds_write2st64_b32 v6, v16, v17 offset0:32 offset1:36
	ds_write2st64_b32 v6, v18, v19 offset0:40 offset1:44
	ds_write2st64_b32 v6, v20, v21 offset0:48 offset1:52
	ds_write2st64_b32 v6, v22, v23 offset0:56 offset1:60
	ds_write2st64_b32 v6, v24, v25 offset0:64 offset1:68
	ds_write2st64_b32 v6, v26, v27 offset0:72 offset1:76
	ds_write2st64_b32 v6, v28, v29 offset0:80 offset1:84
	ds_write2st64_b32 v6, v30, v31 offset0:88 offset1:92
	ds_write2st64_b32 v6, v32, v33 offset0:96 offset1:100
	ds_write2st64_b32 v6, v34, v35 offset0:104 offset1:108
	ds_write2st64_b32 v6, v36, v37 offset0:112 offset1:116
	ds_write2st64_b32 v6, v38, v52 offset0:120 offset1:124
	v_lshlrev_b64 v[10:11], 4, v[130:131]
	s_waitcnt lgkmcnt(0)
	s_barrier
	v_lshl_add_u64 v[6:7], s[12:13], 0, v[10:11]
	v_lshl_add_u64 v[10:11], s[34:35], 0, v[10:11]
	global_load_dwordx4 v[6:9], v[6:7], off
	v_and_b32_e32 v14, 64, v230
	global_load_dwordx4 v[10:13], v[10:11], off
	v_add_u32_e32 v14, 64, v14
	v_xor_b32_e32 v15, 1, v230
	v_cmp_lt_i32_e32 vcc, v15, v14
	v_lshlrev_b32_e32 v22, 4, v130
	v_add3_u32 v22, v50, s88, v22
	v_cndmask_b32_e32 v15, v230, v15, vcc
	v_lshlrev_b32_e32 v16, 2, v15
	v_xor_b32_e32 v15, 2, v230
	v_cmp_lt_i32_e32 vcc, v15, v14
	s_nop 1
	v_cndmask_b32_e32 v15, v230, v15, vcc
	v_lshlrev_b32_e32 v17, 2, v15
	v_xor_b32_e32 v15, 4, v230
	v_cmp_lt_i32_e32 vcc, v15, v14
	s_nop 1
	v_cndmask_b32_e32 v15, v230, v15, vcc
	v_lshlrev_b32_e32 v18, 2, v15
	v_xor_b32_e32 v15, 8, v230
	v_cmp_lt_i32_e32 vcc, v15, v14
	s_nop 1
	v_cndmask_b32_e32 v15, v230, v15, vcc
	v_lshlrev_b32_e32 v19, 2, v15
	v_xor_b32_e32 v15, 16, v230
	v_cmp_lt_i32_e32 vcc, v15, v14
	s_nop 1
	v_cndmask_b32_e32 v15, v230, v15, vcc
	v_lshlrev_b32_e32 v20, 2, v15
	v_xor_b32_e32 v15, 32, v230
	v_cmp_lt_i32_e32 vcc, v15, v14
	s_nop 1
	v_cndmask_b32_e32 v14, v230, v15, vcc
	v_lshlrev_b32_e32 v21, 2, v14
	v_lshlrev_b32_e32 v14, 2, v130
	v_ashrrev_i32_e32 v15, 31, v14
	v_lshl_add_u64 v[14:15], v[14:15], 1, s[4:5]
	s_waitcnt vmcnt(0)

; __device__ __forceinline__ float bf2f(bf16_t b) { return __uint_as_float((unsigned)b << 16); }
; __device__ __forceinline__ bf16_t f2bf(float f) { return (bf16_t)(pk2(f, 0.f) & 0xffffu); }
; __device__ __forceinline__ float fexp(float x) { return __expf(x); }
; __device__ __forceinline__ void gdn_unit(const Ctx& X, LAS unsigned char* hl, int b, int c, int h, int tid_h, int w4, int lane, int layer) {
;     ...
;     {
;         f32x4 acc[4];
;         const float eG63 = fexp(Gs[63]);
; #pragma unroll
;         for (int ct = 0; ct < 4; ++ct) acc[ct] = mma16(P, 16 * w4, WT, 16 * ct, (f32x4){0.f, 0.f, 0.f, 0.f}, r, q);
;         bf16_t* qe = WSP(bf16_t, WS_QEFF) + (size_t)uid * 4096;
; #pragma unroll
;         for (int ct = 0; ct < 4; ++ct)
; #pragma unroll
;             for (int j = 0; j < 4; ++j) { const int ii = 16 * w4 + 4 * q + j, col = 16 * ct + r;
;                 qe[ii * 64 + col] = f2bf(bf2f(Q[ii * LT + col]) * fexp(Gs[ii]) - acc[ct][j]); }
; #pragma unroll
;         for (int ct = 0; ct < 4; ++ct) acc[ct] = mma16(P, 16 * w4, UT, 16 * ct, (f32x4){0.f, 0.f, 0.f, 0.f}, r, q);
.LBB0_619:
	s_waitcnt lgkmcnt(0)
	s_barrier
	v_bfe_u32 v54, v224, 6, 2
	v_and_b32_e32 v55, 15, v232
	v_lshrrev_b32_e32 v56, 4, v232
	v_lshl_or_b32 v57, v54, 4, v55
	v_mul_u32_u24_e32 v58, 0x90, v57
	v_mul_u32_u24_e32 v59, 0x90, v55
	v_lshl_add_u32 v60, v56, 4, v58
	v_lshl_add_u32 v61, v56, 4, v59
	v_add_u32_e32 v60, v182, v60
	v_add_u32_e32 v61, v182, v61
	v_add_u32_e32 v178, 0xb400, v60
	v_add_u32_e32 v179, 0x4800, v61
	v_add_u32_e32 v60, 0x9000, v60
	v_add_u32_e32 v61, 0x6c00, v61
	ds_read_b128 v[6:9], v178
	ds_read_b128 v[10:13], v178 offset:64
	ds_read_b128 v[22:25], v179
	ds_read_b128 v[26:29], v179 offset:64
	ds_read_b128 v[30:33], v179 offset:2304
	ds_read_b128 v[34:37], v179 offset:2368
	ds_read_b128 v[38:41], v179 offset:4608
	ds_read_b128 v[42:45], v179 offset:4672
	ds_read_b128 v[46:49], v179 offset:6912
	ds_read_b128 v[50:53], v179 offset:6976
	ds_read_b128 v[14:17], v60
	ds_read_b128 v[18:21], v60 offset:64
	v_lshl_add_u32 v62, v57, 2, v185
	v_lshl_add_u32 v63, v56, 3, v58
	v_add_u32_e32 v63, v182, v63
	ds_read_b32 v176, v62
	ds_read_b32 v177, v185 offset:252
	s_lshl_b32 s0, s22, 9
	s_lshl_b32 s1, s23, 7
	s_add_i32 s1, s1, s0
	s_or_b32 s0, s1, s21
	s_ashr_i32 s1, s0, 31
	s_lshl_b64 s[0:1], s[0:1], 13
	s_add_u32 s4, s89, s0
	s_addc_u32 s5, s78, s1
	s_add_u32 s6, s79, s0
	s_addc_u32 s7, s80, s1
	v_readlane_b32 s98, v253, 3
	v_readlane_b32 s99, v253, 4
	s_add_u32 s98, s98, s0
	s_addc_u32 s99, s99, s1
	s_add_u32 s98, s98, 0xff000000
	s_addc_u32 s99, s99, -1
	s_add_u32 s100, s74, s0
	s_addc_u32 s101, s75, s1
	v_readfirstlane_b32 s32, v54
	v_lshlrev_b32_e32 v64, 11, v54
	v_lshlrev_b32_e32 v65, 5, v232
	v_lshl_add_u32 v64, v232, 4, v64
	v_lshlrev_b32_e32 v66, 9, v54
	v_lshl_add_u32 v66, v232, 3, v66
	v_add_u32_e32 v67, 0x1000, v66
	v_lshlrev_b32_e32 v71, 7, v57
	v_lshl_add_u32 v71, v56, 3, v71
	v_lshlrev_b32_e32 v70, 2, v56
	v_sub_u32_e32 v70, v55, v70
	s_waitcnt lgkmcnt(4)
	v_mfma_f32_16x16x32_bf16 v[134:137], v[22:25], v[6:9], 0
	v_mfma_f32_16x16x32_bf16 v[138:141], v[30:33], v[6:9], 0
	v_mfma_f32_16x16x32_bf16 v[142:145], v[38:41], v[6:9], 0
	v_mfma_f32_16x16x32_bf16 v[146:149], v[46:49], v[6:9], 0
	v_mfma_f32_16x16x32_bf16 v[134:137], v[26:29], v[10:13], v[134:137]
	v_mfma_f32_16x16x32_bf16 v[138:141], v[34:37], v[10:13], v[138:141]
	v_mfma_f32_16x16x32_bf16 v[142:145], v[42:45], v[10:13], v[142:145]
	v_mfma_f32_16x16x32_bf16 v[146:149], v[50:53], v[10:13], v[146:149]
	ds_read_b64 v[150:151], v63
	ds_read_b64 v[152:153], v63 offset:32
	ds_read_b64 v[172:173], v63 offset:64
	ds_read_b64 v[174:175], v63 offset:96
	ds_read_b128 v[186:189], v61
	ds_read_b128 v[190:193], v61 offset:64
	ds_read_b128 v[194:197], v61 offset:2304
	ds_read_b128 v[198:201], v61 offset:2368
	ds_read_b128 v[202:205], v61 offset:4608
	ds_read_b128 v[206:209], v61 offset:4672
	ds_read_b128 v[210:213], v61 offset:6912
	s_waitcnt lgkmcnt(13)
	v_mfma_f32_16x16x32_bf16 v[236:239], v[22:25], v[14:17], 0
	v_mfma_f32_16x16x32_bf16 v[240:243], v[30:33], v[14:17], 0
	v_mfma_f32_16x16x32_bf16 v[244:247], v[38:41], v[14:17], 0
	v_mfma_f32_16x16x32_bf16 v[248:251], v[46:49], v[14:17], 0
	v_mfma_f32_16x16x32_bf16 v[236:239], v[26:29], v[18:21], v[236:239]
	v_mfma_f32_16x16x32_bf16 v[240:243], v[34:37], v[18:21], v[240:243]
	v_mfma_f32_16x16x32_bf16 v[244:247], v[42:45], v[18:21], v[244:247]
	v_mfma_f32_16x16x32_bf16 v[248:251], v[50:53], v[18:21], v[248:251]
	ds_read_b128 v[214:217], v61 offset:6976
	s_waitcnt lgkmcnt(8)
	v_mul_f32_e32 v176, 0x3fb8aa3b, v176
	v_mul_f32_e32 v177, 0x3fb8aa3b, v177
	v_exp_f32_e32 v176, v176
	v_exp_f32_e32 v177, v177
	v_cmp_eq_u32_e32 vcc, 0, v70
	v_cmp_eq_u32_e64 s[0:1], 1, v70
	v_lshlrev_b32_e32 v76, 16, v150
	v_and_b32_e32 v77, 0xffff0000, v150
	v_cndmask_b32_e32 v72, 0, v177, vcc
	v_cndmask_b32_e64 v73, 0, v177, s[0:1]
	v_cmp_eq_u32_e32 vcc, 2, v70
	v_cmp_eq_u32_e64 s[0:1], 3, v70
	v_lshlrev_b32_e32 v78, 16, v151
	v_and_b32_e32 v79, 0xffff0000, v151
	v_cndmask_b32_e32 v74, 0, v177, vcc
	v_cndmask_b32_e64 v75, 0, v177, s[0:1]
	s_waitcnt lgkmcnt(0)
; __device__ __forceinline__ float bf2f(bf16_t b) { return __uint_as_float((unsigned)b << 16); }
; __device__ __forceinline__ bf16_t f2bf(float f) { return (bf16_t)(pk2(f, 0.f) & 0xffffu); }
; __device__ __forceinline__ float fexp(float x) { return __expf(x); }
; __device__ __forceinline__ void gdn_unit(const Ctx& X, LAS unsigned char* hl, int b, int c, int h, int tid_h, int w4, int lane, int layer) {
;     ...
;         bf16_t* qe = WSP(bf16_t, WS_QEFF) + (size_t)uid * 4096;
; #pragma unroll
;         for (int ct = 0; ct < 4; ++ct)
; #pragma unroll
;             for (int j = 0; j < 4; ++j) { const int ii = 16 * w4 + 4 * q + j, col = 16 * ct + r;
;                 qe[ii * 64 + col] = f2bf(bf2f(Q[ii * LT + col]) * fexp(Gs[ii]) - acc[ct][j]); }
; #pragma unroll
;         for (int ct = 0; ct < 4; ++ct) acc[ct] = mma16(P, 16 * w4, UT, 16 * ct, (f32x4){0.f, 0.f, 0.f, 0.f}, r, q);
;         store_oloc(WSP(bf16_t, WS_OLOC), uid, w4, lane, acc);
; #pragma unroll
;         for (int ct = 0; ct < 4; ++ct) acc[ct] = mma16(KDT, 16 * w4, WT, 16 * ct, (f32x4){0.f, 0.f, 0.f, 0.f}, r, q);
;         bf16_t* mm = WSP(bf16_t, WS_MM) + (size_t)(uid - 2048) * 4096;
; #pragma unroll
;         for (int ct = 0; ct < 4; ++ct)
; #pragma unroll
;             for (int j = 0; j < 4; ++j) { const int ii = 16 * w4 + 4 * q + j, col = 16 * ct + r;
;                 mm[((w4 * 2 + (ct >> 1)) * 64 + (r >> 2) * 16 + 4 * q + j) * 8 + (ct & 1) * 4 + (r & 3)] = f2bf((ii == col ? eG63 : 0.f) - acc[ct][j]); }
; #pragma unroll
;         for (int ct = 0; ct < 4; ++ct) acc[ct] = mma16(KDT, 16 * w4, UT, 16 * ct, (f32x4){0.f, 0.f, 0.f, 0.f}, r, q);
;         store_bc(WSP(bf16_t, WS_BCS), uid, w4, r, q, acc);
;     }
	v_mfma_f32_16x16x32_bf16 v[84:87], v[6:9], v[186:189], 0
	v_mfma_f32_16x16x32_bf16 v[88:91], v[6:9], v[194:197], 0
	v_mfma_f32_16x16x32_bf16 v[92:95], v[6:9], v[202:205], 0
	v_mfma_f32_16x16x32_bf16 v[96:99], v[6:9], v[210:213], 0
	v_mfma_f32_16x16x32_bf16 v[114:117], v[14:17], v[186:189], 0
	v_mfma_f32_16x16x32_bf16 v[118:121], v[14:17], v[194:197], 0
	v_mfma_f32_16x16x32_bf16 v[122:125], v[14:17], v[202:205], 0
	v_mfma_f32_16x16x32_bf16 v[126:129], v[14:17], v[210:213], 0
	v_mfma_f32_16x16x32_bf16 v[84:87], v[10:13], v[190:193], v[84:87]
	v_mfma_f32_16x16x32_bf16 v[88:91], v[10:13], v[198:201], v[88:91]
	v_mfma_f32_16x16x32_bf16 v[92:95], v[10:13], v[206:209], v[92:95]
	v_mfma_f32_16x16x32_bf16 v[96:99], v[10:13], v[214:217], v[96:99]
	v_mfma_f32_16x16x32_bf16 v[114:117], v[18:21], v[190:193], v[114:117]
	v_mfma_f32_16x16x32_bf16 v[118:121], v[18:21], v[198:201], v[118:121]
	v_mfma_f32_16x16x32_bf16 v[122:125], v[18:21], v[206:209], v[122:125]
	v_mfma_f32_16x16x32_bf16 v[126:129], v[18:21], v[214:217], v[126:129]
	v_fma_f32 v76, v176, v76, -v134
	v_fma_f32 v77, v176, v77, -v135
	v_fma_f32 v78, v176, v78, -v136
	v_fma_f32 v79, v176, v79, -v137
	v_cvt_pk_bf16_f32 v218, v76, v77
	v_cvt_pk_bf16_f32 v219, v78, v79
	global_store_dwordx2 v71, v[218:219], s[4:5]
	v_lshlrev_b32_e32 v76, 16, v152
	v_and_b32_e32 v77, 0xffff0000, v152
	v_lshlrev_b32_e32 v78, 16, v153
	v_and_b32_e32 v79, 0xffff0000, v153
	v_fma_f32 v76, v176, v76, -v138
	v_fma_f32 v77, v176, v77, -v139
	v_fma_f32 v78, v176, v78, -v140
	v_fma_f32 v79, v176, v79, -v141
	v_cvt_pk_bf16_f32 v220, v76, v77
	v_cvt_pk_bf16_f32 v221, v78, v79
	global_store_dwordx2 v71, v[220:221], s[4:5] offset:32
	v_lshlrev_b32_e32 v76, 16, v172
	v_and_b32_e32 v77, 0xffff0000, v172
	v_lshlrev_b32_e32 v78, 16, v173
	v_and_b32_e32 v79, 0xffff0000, v173
	v_fma_f32 v76, v176, v76, -v142
	v_fma_f32 v77, v176, v77, -v143
	v_fma_f32 v78, v176, v78, -v144
	v_fma_f32 v79, v176, v79, -v145
	v_cvt_pk_bf16_f32 v222, v76, v77
	v_cvt_pk_bf16_f32 v223, v78, v79
	global_store_dwordx2 v71, v[222:223], s[4:5] offset:64
	v_lshlrev_b32_e32 v76, 16, v174
	v_and_b32_e32 v77, 0xffff0000, v174
	v_lshlrev_b32_e32 v78, 16, v175
	v_and_b32_e32 v79, 0xffff0000, v175
	v_fma_f32 v76, v176, v76, -v146
	v_fma_f32 v77, v176, v77, -v147
	v_fma_f32 v78, v176, v78, -v148
	v_fma_f32 v79, v176, v79, -v149
	v_cvt_pk_bf16_f32 v226, v76, v77
	v_cvt_pk_bf16_f32 v227, v78, v79
	global_store_dwordx2 v71, v[226:227], s[4:5] offset:96
	s_cmp_eq_u32 s32, 0
	s_cselect_b32 s0, 1.0, 0
	v_fma_f32 v76, v72, s0, -v236
	v_fma_f32 v77, v73, s0, -v237
	v_fma_f32 v78, v74, s0, -v238
	v_fma_f32 v79, v75, s0, -v239
	v_cvt_pk_bf16_f32 v100, v76, v77
	v_cvt_pk_bf16_f32 v101, v78, v79
	s_cmp_eq_u32 s32, 1
	s_cselect_b32 s0, 1.0, 0
	v_fma_f32 v76, v72, s0, -v240
	v_fma_f32 v77, v73, s0, -v241
	v_fma_f32 v78, v74, s0, -v242
	v_fma_f32 v79, v75, s0, -v243
	v_cvt_pk_bf16_f32 v102, v76, v77
	v_cvt_pk_bf16_f32 v103, v78, v79
	global_store_dwordx4 v64, v[100:103], s[98:99]
	s_cmp_eq_u32 s32, 2
	s_cselect_b32 s0, 1.0, 0
	v_fma_f32 v76, v72, s0, -v244
	v_fma_f32 v77, v73, s0, -v245
	v_fma_f32 v78, v74, s0, -v246
	v_fma_f32 v79, v75, s0, -v247
	v_cvt_pk_bf16_f32 v104, v76, v77
	v_cvt_pk_bf16_f32 v105, v78, v79
	s_cmp_eq_u32 s32, 3
	s_cselect_b32 s0, 1.0, 0
	v_fma_f32 v76, v72, s0, -v248
	v_fma_f32 v77, v73, s0, -v249
	v_fma_f32 v78, v74, s0, -v250
	v_fma_f32 v79, v75, s0, -v251
	v_cvt_pk_bf16_f32 v106, v76, v77
	v_cvt_pk_bf16_f32 v107, v78, v79
	global_store_dwordx4 v64, v[104:107], s[98:99] offset:1024
	v_cvt_pk_bf16_f32 v108, v84, v85
	v_cvt_pk_bf16_f32 v109, v86, v87
	v_cvt_pk_bf16_f32 v110, v88, v89
	v_cvt_pk_bf16_f32 v111, v90, v91
	global_store_dwordx4 v65, v[108:111], s[6:7] nt
	v_cvt_pk_bf16_f32 v80, v92, v93
	v_cvt_pk_bf16_f32 v81, v94, v95
	v_cvt_pk_bf16_f32 v82, v96, v97
	v_cvt_pk_bf16_f32 v83, v98, v99
	global_store_dwordx4 v65, v[80:83], s[6:7] offset:16 nt
	v_cvt_pk_bf16_f32 v40, v114, v115
	v_cvt_pk_bf16_f32 v41, v116, v117
	global_store_dwordx2 v66, v[40:41], s[100:101]
	v_cvt_pk_bf16_f32 v42, v118, v119
	v_cvt_pk_bf16_f32 v43, v120, v121
	global_store_dwordx2 v66, v[42:43], s[100:101] offset:2048
	v_cvt_pk_bf16_f32 v44, v122, v123
	v_cvt_pk_bf16_f32 v45, v124, v125
	global_store_dwordx2 v67, v[44:45], s[100:101]
	v_cvt_pk_bf16_f32 v46, v126, v127
	v_cvt_pk_bf16_f32 v47, v128, v129
	global_store_dwordx2 v67, v[46:47], s[100:101] offset:2048
	s_branch .Lgdn_p4_pad_end
	s_nop 0
	s_nop 0
	s_nop 0
	s_nop 0
	s_nop 0
	s_nop 0
	s_nop 0
	s_nop 0
	s_nop 0
	s_nop 0
	s_nop 0
	s_nop 0
	s_nop 0
	s_nop 0
	s_nop 0
	s_nop 0
	s_nop 0
	s_nop 0
	s_nop 0
	s_nop 0
	s_nop 0
	s_nop 0
	s_nop 0
	s_nop 0
	s_nop 0
	s_nop 0
	s_nop 0
	s_nop 0
	s_nop 0
	s_nop 0
	s_nop 0
	s_nop 0
	s_nop 0
	s_nop 0
	s_nop 0
	s_nop 0
	s_nop 0
	s_nop 0
	s_nop 0
	s_nop 0
	s_nop 0
	s_nop 0
	s_nop 0
	s_nop 0
	s_nop 0
	s_nop 0
	s_nop 0
	s_nop 0
	s_nop 0
	s_nop 0
	s_nop 0
	s_nop 0
	s_nop 0
	s_nop 0
	s_nop 0
	s_nop 0
	s_nop 0
	s_nop 0
	s_nop 0
	s_nop 0
	s_nop 0
	s_nop 0
	s_nop 0
	s_nop 0
	s_nop 0
	s_nop 0
	s_nop 0
	s_nop 0
	s_nop 0
	s_nop 0
	s_nop 0
	s_nop 0
	s_nop 0
	s_nop 0
	s_nop 0
	s_nop 0
	s_nop 0
	s_nop 0
	s_nop 0
	s_nop 0
	s_nop 0
	s_nop 0
	s_nop 0
	s_nop 0
	s_nop 0
	s_nop 0
	s_nop 0
	s_nop 0
	s_nop 0
	s_nop 0
	s_nop 0
	s_nop 0
	s_nop 0
	s_nop 0
	s_nop 0
	s_nop 0
	s_nop 0
	s_nop 0
	s_nop 0
	s_nop 0
	s_nop 0
	s_nop 0
	s_nop 0
	s_nop 0
	s_nop 0
	s_nop 0
	s_nop 0
	s_nop 0
	s_nop 0
	s_nop 0
	s_nop 0
	s_nop 0
	s_nop 0
	s_nop 0
	s_nop 0
	s_nop 0
	s_nop 0
	s_nop 0
	s_nop 0
	s_nop 0
	s_nop 0
	s_nop 0
	s_nop 0
	s_nop 0
	s_nop 0
	s_nop 0
	s_nop 0
	s_nop 0
	s_nop 0
	s_nop 0
	s_nop 0
	s_nop 0
	s_nop 0
	s_nop 0
	s_nop 0
	s_nop 0
	s_nop 0
	s_nop 0
	s_nop 0
	s_nop 0
	s_nop 0
	s_nop 0
	s_nop 0
	s_nop 0
	s_nop 0
	s_nop 0
	s_nop 0
	s_nop 0
	s_nop 0
	s_nop 0
	s_nop 0
	s_nop 0
	s_nop 0
	s_nop 0
	s_nop 0
	s_nop 0
	s_nop 0
	s_nop 0
	s_nop 0
	s_nop 0
	s_nop 0
	s_nop 0
	s_nop 0
	s_nop 0
	s_nop 0
	s_nop 0
	s_nop 0
	s_nop 0
	s_nop 0
	s_nop 0
	s_nop 0
	s_nop 0
	s_nop 0
	s_nop 0
	s_nop 0
	s_nop 0
	s_nop 0
	s_nop 0
	s_nop 0
	s_nop 0
	s_nop 0
	s_nop 0
	s_nop 0
	s_nop 0
	s_nop 0
	s_nop 0
	s_nop 0
	s_nop 0
	s_nop 0
	s_nop 0
	s_nop 0
	s_nop 0
	s_nop 0
	s_nop 0
	s_nop 0
	s_nop 0
	s_nop 0
	s_nop 0
	s_nop 0
	s_nop 0
	s_nop 0
	s_nop 0
	s_nop 0
	s_nop 0
	s_nop 0
	s_nop 0
	s_nop 0
	s_nop 0
	s_nop 0
	s_nop 0
	s_nop 0
	s_nop 0
	s_nop 0
	s_nop 0
	s_nop 0
	s_nop 0
	s_nop 0
	s_nop 0
	s_nop 0
	s_nop 0
	s_nop 0
	s_nop 0
	s_nop 0
	s_nop 0
	s_nop 0
	s_nop 0
	s_nop 0
	s_nop 0
	s_nop 0
	s_nop 0
	s_nop 0
	s_nop 0
	s_nop 0
	s_nop 0
	s_nop 0
	s_nop 0
	s_nop 0
	s_nop 0
	s_nop 0
	s_nop 0
	s_nop 0
	s_nop 0
.Lgdn_p4_pad_end:
	s_waitcnt lgkmcnt(0)
	s_barrier
	s_mov_b64 s[0:1], 0
